# attention softmax: packed row-sum adds between MFMAs split into single v_add_f32 (bit-identical)
# speedup vs baseline: 1.0133x; 1.0106x over previous
.Lat_nme:
	v_add_u32_e32 v184, 0xffffffc0, v184
	v_max_f32_e32 v200, v65, v65
	s_waitcnt lgkmcnt(6)
	v_mfma_f32_32x32x16_bf16 v[32:47], v[204:207], v[220:223], v[32:47]
	ds_read_b64_tr_b16 v[220:221], v165 offset:512
	ds_read_b64_tr_b16 v[222:223], v165 offset:2560
	v_max_f32_e32 v201, v64, v64
	v_max_f32_e32 v200, v201, v200
	v_max3_f32 v200, v200, v66, v67
	v_max3_f32 v200, v200, v68, v69
	v_max3_f32 v200, v200, v70, v71
	s_waitcnt lgkmcnt(6)
	v_mfma_f32_32x32x16_bf16 v[32:47], v[208:211], v[224:227], v[32:47]
	ds_read_b64_tr_b16 v[224:225], v165 offset:4608
	ds_read_b64_tr_b16 v[226:227], v165 offset:6656
	v_max3_f32 v200, v200, v72, v73
	v_max3_f32 v200, v200, v74, v75
	v_max3_f32 v200, v200, v76, v77
	v_max3_f32 v200, v200, v78, v79
	v_max3_f32 v200, v200, v80, v81
	s_waitcnt lgkmcnt(6)
	v_mfma_f32_32x32x16_bf16 v[32:47], v[212:215], v[228:231], v[32:47]
	ds_read_b64_tr_b16 v[228:229], v165 offset:8704
	ds_read_b64_tr_b16 v[230:231], v165 offset:10752
	v_max3_f32 v200, v200, v82, v83
	v_max3_f32 v200, v200, v84, v85
	v_max3_f32 v200, v200, v86, v87
	v_max3_f32 v200, v200, v88, v89
	s_waitcnt lgkmcnt(6)
	v_mfma_f32_32x32x16_bf16 v[32:47], v[216:219], v[232:235], v[32:47]
	ds_read_b64_tr_b16 v[232:233], v165 offset:12800
	ds_read_b64_tr_b16 v[234:235], v165 offset:14848
	v_max3_f32 v200, v200, v90, v91
	v_max3_f32 v200, v200, v92, v93
	v_max3_f32 v200, v200, v94, v95
	v_mov_b32_e32 v201, v200
	s_nop 1
	s_waitcnt lgkmcnt(6)
	v_mfma_f32_32x32x16_bf16 v[48:63], v[204:207], v[220:223], v[48:63]
	ds_read_b64_tr_b16 v[220:221], v165 offset:1024
	ds_read_b64_tr_b16 v[222:223], v165 offset:3072
	v_permlane32_swap_b32_e32 v200, v201
	v_max_f32_e32 v201, v201, v201
	v_max_f32_e32 v200, v200, v200
	v_max_f32_e32 v200, v200, v201
	v_sub_f32_e32 v201, v200, v203
	s_waitcnt lgkmcnt(6)
	v_mfma_f32_32x32x16_bf16 v[48:63], v[208:211], v[224:227], v[48:63]
	ds_read_b64_tr_b16 v[224:225], v165 offset:5120
	ds_read_b64_tr_b16 v[226:227], v165 offset:7168
	v_mul_f32_e32 v201, 0x3db504f3, v201
	v_cmp_ge_f32_e32 vcc, 0x41000000, v201
	v_max_f32_e32 v201, v203, v203
	v_max_f32_e32 v200, v201, v200
	s_waitcnt lgkmcnt(6)
	v_mfma_f32_32x32x16_bf16 v[48:63], v[212:215], v[228:231], v[48:63]
	ds_read_b64_tr_b16 v[228:229], v165 offset:9216
	ds_read_b64_tr_b16 v[230:231], v165 offset:11264
	v_sub_f32_e32 v201, v203, v200
	v_mul_f32_e32 v201, 0x3e0293ee, v201
	v_exp_f32_e32 v201, v201
	s_cmp_eq_u64 vcc, exec
	s_cselect_b64 s[44:45], -1, 0
	s_waitcnt lgkmcnt(6)
	v_mfma_f32_32x32x16_bf16 v[48:63], v[216:219], v[232:235], v[48:63]
	ds_read_b64_tr_b16 v[232:233], v165 offset:13312
	ds_read_b64_tr_b16 v[234:235], v165 offset:15360
	v_cndmask_b32_e64 v202, v201, 1.0, s[44:45]
	v_cndmask_b32_e64 v203, v200, v203, s[44:45]
	v_mul_f32_e32 v248, 0xbe0293ee, v203
	v_pk_fma_f32 v[64:65], v[64:65], s[10:11], v[248:249] op_sel_hi:[1,0,0]
	v_pk_fma_f32 v[66:67], v[66:67], s[10:11], v[248:249] op_sel_hi:[1,0,0]
	s_waitcnt lgkmcnt(6)
	v_mfma_f32_32x32x16_bf16 v[16:31], v[204:207], v[220:223], v[16:31]
	ds_read_b64_tr_b16 v[220:221], v165 offset:1536
	ds_read_b64_tr_b16 v[222:223], v165 offset:3584
	v_pk_fma_f32 v[68:69], v[68:69], s[10:11], v[248:249] op_sel_hi:[1,0,0]
	v_pk_fma_f32 v[70:71], v[70:71], s[10:11], v[248:249] op_sel_hi:[1,0,0]
	v_pk_fma_f32 v[72:73], v[72:73], s[10:11], v[248:249] op_sel_hi:[1,0,0]
	v_pk_fma_f32 v[74:75], v[74:75], s[10:11], v[248:249] op_sel_hi:[1,0,0]
	s_waitcnt lgkmcnt(6)
	v_mfma_f32_32x32x16_bf16 v[16:31], v[208:211], v[224:227], v[16:31]
	ds_read_b64_tr_b16 v[224:225], v165 offset:5632
	ds_read_b64_tr_b16 v[226:227], v165 offset:7680
	v_pk_fma_f32 v[76:77], v[76:77], s[10:11], v[248:249] op_sel_hi:[1,0,0]
	v_pk_fma_f32 v[78:79], v[78:79], s[10:11], v[248:249] op_sel_hi:[1,0,0]
	v_pk_fma_f32 v[80:81], v[80:81], s[10:11], v[248:249] op_sel_hi:[1,0,0]
	v_pk_fma_f32 v[82:83], v[82:83], s[10:11], v[248:249] op_sel_hi:[1,0,0]
	v_pk_fma_f32 v[84:85], v[84:85], s[10:11], v[248:249] op_sel_hi:[1,0,0]
	s_waitcnt lgkmcnt(6)
	v_mfma_f32_32x32x16_bf16 v[16:31], v[212:215], v[228:231], v[16:31]
	ds_read_b64_tr_b16 v[228:229], v165 offset:9728
	ds_read_b64_tr_b16 v[230:231], v165 offset:11776
	v_pk_fma_f32 v[86:87], v[86:87], s[10:11], v[248:249] op_sel_hi:[1,0,0]
	v_pk_fma_f32 v[88:89], v[88:89], s[10:11], v[248:249] op_sel_hi:[1,0,0]
	v_pk_fma_f32 v[90:91], v[90:91], s[10:11], v[248:249] op_sel_hi:[1,0,0]
	v_pk_fma_f32 v[92:93], v[92:93], s[10:11], v[248:249] op_sel_hi:[1,0,0]
	v_pk_fma_f32 v[94:95], v[94:95], s[10:11], v[248:249] op_sel_hi:[1,0,0]
	s_waitcnt lgkmcnt(6)
	v_mfma_f32_32x32x16_bf16 v[16:31], v[216:219], v[232:235], v[16:31]
	ds_read_b64_tr_b16 v[232:233], v165 offset:13824
	ds_read_b64_tr_b16 v[234:235], v165 offset:15872
	v_exp_f32_e32 v64, v64
	v_exp_f32_e32 v65, v65
	v_exp_f32_e32 v66, v66
	v_exp_f32_e32 v67, v67
	s_waitcnt lgkmcnt(6)
	v_mfma_f32_32x32x16_bf16 v[0:15], v[204:207], v[220:223], v[0:15]
	v_exp_f32_e32 v68, v68
	v_exp_f32_e32 v69, v69
	v_add_f32_e32 v170, v64, v66
	v_add_f32_e32 v171, v65, v67
	v_exp_f32_e32 v70, v70
	v_exp_f32_e32 v71, v71
	s_waitcnt lgkmcnt(4)
	v_mfma_f32_32x32x16_bf16 v[0:15], v[208:211], v[224:227], v[0:15]
	v_add_f32_e32 v170, v170, v68
	v_add_f32_e32 v171, v171, v69
	v_exp_f32_e32 v72, v72
	v_exp_f32_e32 v73, v73
	v_add_f32_e32 v170, v170, v70
	v_add_f32_e32 v171, v171, v71
	v_exp_f32_e32 v74, v74
	s_waitcnt lgkmcnt(2)
	v_mfma_f32_32x32x16_bf16 v[0:15], v[212:215], v[228:231], v[0:15]
	v_exp_f32_e32 v75, v75
	v_add_f32_e32 v170, v170, v72
	v_add_f32_e32 v171, v171, v73
	v_exp_f32_e32 v76, v76
	v_exp_f32_e32 v77, v77
	s_waitcnt lgkmcnt(0)
	v_mfma_f32_32x32x16_bf16 v[0:15], v[216:219], v[232:235], v[0:15]
	v_add_f32_e32 v170, v170, v74
	v_add_f32_e32 v171, v171, v75
	v_exp_f32_e32 v78, v78
	v_exp_f32_e32 v79, v79
	v_add_f32_e32 v170, v170, v76
	v_add_f32_e32 v171, v171, v77
	v_cmp_gt_f32_e32 vcc, 1.0, v202
	s_cbranch_vccz .Lat_nre
	s_nop 7
	s_nop 7
	s_and_saveexec_b64 s[4:5], s[0:1]
	ds_write_b32 v183, v202
	s_or_b64 exec, exec, s[4:5]
	s_waitcnt lgkmcnt(0)
	ds_read_b128 v[244:247], v177 offset:0
	s_waitcnt lgkmcnt(0)
	v_pk_mul_f32 v[32:33], v[32:33], v[244:245]
	v_pk_mul_f32 v[34:35], v[34:35], v[246:247]
	v_pk_mul_f32 v[48:49], v[48:49], v[244:245]
	v_pk_mul_f32 v[50:51], v[50:51], v[246:247]
	v_pk_mul_f32 v[16:17], v[16:17], v[244:245]
	v_pk_mul_f32 v[18:19], v[18:19], v[246:247]
	v_pk_mul_f32 v[0:1], v[0:1], v[244:245]
	v_pk_mul_f32 v[2:3], v[2:3], v[246:247]
	ds_read_b128 v[244:247], v177 offset:32
	s_waitcnt lgkmcnt(0)
	v_pk_mul_f32 v[36:37], v[36:37], v[244:245]
	v_pk_mul_f32 v[38:39], v[38:39], v[246:247]
	v_pk_mul_f32 v[52:53], v[52:53], v[244:245]
	v_pk_mul_f32 v[54:55], v[54:55], v[246:247]
	v_pk_mul_f32 v[20:21], v[20:21], v[244:245]
	v_pk_mul_f32 v[22:23], v[22:23], v[246:247]
	v_pk_mul_f32 v[4:5], v[4:5], v[244:245]
	v_pk_mul_f32 v[6:7], v[6:7], v[246:247]
	ds_read_b128 v[244:247], v177 offset:64
	s_waitcnt lgkmcnt(0)
	v_pk_mul_f32 v[40:41], v[40:41], v[244:245]
	v_pk_mul_f32 v[42:43], v[42:43], v[246:247]
	v_pk_mul_f32 v[56:57], v[56:57], v[244:245]
	v_pk_mul_f32 v[58:59], v[58:59], v[246:247]
	v_pk_mul_f32 v[24:25], v[24:25], v[244:245]
	v_pk_mul_f32 v[26:27], v[26:27], v[246:247]
	v_pk_mul_f32 v[8:9], v[8:9], v[244:245]
	v_pk_mul_f32 v[10:11], v[10:11], v[246:247]
	ds_read_b128 v[244:247], v177 offset:96
	s_waitcnt lgkmcnt(0)
	v_pk_mul_f32 v[44:45], v[44:45], v[244:245]
	v_pk_mul_f32 v[46:47], v[46:47], v[246:247]
	v_pk_mul_f32 v[60:61], v[60:61], v[244:245]
	v_pk_mul_f32 v[62:63], v[62:63], v[246:247]
	v_pk_mul_f32 v[28:29], v[28:29], v[244:245]
	v_pk_mul_f32 v[30:31], v[30:31], v[246:247]
	v_pk_mul_f32 v[12:13], v[12:13], v[244:245]
	v_pk_mul_f32 v[14:15], v[14:15], v[246:247]
.Lat_nre:
	s_waitcnt lgkmcnt(0)
	s_barrier
	v_xor_b32_e32 v186, 0x80, v186
	v_xor_b32_e32 v187, 0x80, v187
	v_xor_b32_e32 v188, 0x80, v188
	v_xor_b32_e32 v189, 0x80, v189
	ds_read_b128 v[236:239], v186 offset:49152
	ds_read_b128 v[240:243], v186 offset:57344
	v_cvt_f32_u32_e32 v204, s13
	v_mov_b32_e32 v165, v164
	v_fma_f32 v204, v172, v204, v179
	v_add_f32_e32 v208, v173, v204
	v_add_f32_e32 v212, v173, v208
	v_add_f32_e32 v216, v173, v212
	v_add_f32_e32 v205, v172, v204
	v_add_f32_e32 v209, v172, v208
	v_add_f32_e32 v213, v172, v212
	v_add_f32_e32 v217, v172, v216
	v_pk_add_f32 v[206:207], v[162:163], v[204:205] op_sel_hi:[1,0]
	v_pk_add_f32 v[210:211], v[162:163], v[208:209] op_sel_hi:[1,0]
	v_pk_add_f32 v[214:215], v[162:163], v[212:213] op_sel_hi:[1,0]
	v_pk_add_f32 v[218:219], v[162:163], v[216:217] op_sel_hi:[1,0]
	v_pk_add_f32 v[222:223], v[164:165], v[206:207]
	v_pk_add_f32 v[220:221], v[166:167], v[204:205]
	v_pk_add_f32 v[226:227], v[164:165], v[210:211]
	v_pk_add_f32 v[224:225], v[164:165], v[208:209]
	v_pk_add_f32 v[230:231], v[164:165], v[214:215]
	v_pk_add_f32 v[228:229], v[164:165], v[212:213]
	v_pk_add_f32 v[234:235], v[164:165], v[218:219]
	v_pk_add_f32 v[232:233], v[164:165], v[216:217]
	s_addk_i32 s13, 0x40
	v_exp_f32_e32 v80, v80
	s_waitcnt lgkmcnt(1)
	v_mfma_f32_32x32x16_bf16 v[204:219], v[236:239], v[104:107], v[204:219]
	ds_read_b128 v[236:239], v187 offset:49152
	v_exp_f32_e32 v81, v81
	v_add_f32_e32 v170, v170, v78
	v_add_f32_e32 v171, v171, v79
	v_exp_f32_e32 v82, v82
	s_waitcnt lgkmcnt(1)
	v_mfma_f32_32x32x16_bf16 v[220:235], v[240:243], v[104:107], v[220:235]
	ds_read_b128 v[240:243], v187 offset:57344
	v_exp_f32_e32 v83, v83
	v_add_f32_e32 v170, v170, v80
	v_add_f32_e32 v171, v171, v81
	v_exp_f32_e32 v84, v84
	v_exp_f32_e32 v85, v85
	s_waitcnt lgkmcnt(1)
	v_mfma_f32_32x32x16_bf16 v[204:219], v[236:239], v[108:111], v[204:219]
	ds_read_b128 v[236:239], v188 offset:49152
	v_add_f32_e32 v170, v170, v82
	v_add_f32_e32 v171, v171, v83
	v_exp_f32_e32 v86, v86
	v_exp_f32_e32 v87, v87
	s_waitcnt lgkmcnt(1)
	v_mfma_f32_32x32x16_bf16 v[220:235], v[240:243], v[108:111], v[220:235]
	ds_read_b128 v[240:243], v188 offset:57344
	v_add_f32_e32 v170, v170, v84
	v_add_f32_e32 v171, v171, v85
	v_exp_f32_e32 v88, v88
	v_exp_f32_e32 v89, v89
	v_add_f32_e32 v170, v170, v86
	v_add_f32_e32 v171, v171, v87
	s_waitcnt lgkmcnt(1)
	v_mfma_f32_32x32x16_bf16 v[204:219], v[236:239], v[112:115], v[204:219]
	ds_read_b128 v[236:239], v189 offset:49152
	v_exp_f32_e32 v90, v90
	v_exp_f32_e32 v91, v91
	v_add_f32_e32 v170, v170, v88
	v_add_f32_e32 v171, v171, v89
	v_exp_f32_e32 v92, v92
	s_waitcnt lgkmcnt(1)
	v_mfma_f32_32x32x16_bf16 v[220:235], v[240:243], v[112:115], v[220:235]
	ds_read_b128 v[240:243], v189 offset:57344
	v_exp_f32_e32 v93, v93
	v_add_f32_e32 v170, v170, v90
	v_add_f32_e32 v171, v171, v91
	v_exp_f32_e32 v94, v94
	s_waitcnt lgkmcnt(1)
	v_mfma_f32_32x32x16_bf16 v[204:219], v[236:239], v[116:119], v[204:219]
	v_xor_b32_e32 v186, 0x80, v186
	v_xor_b32_e32 v187, 0x80, v187
	v_xor_b32_e32 v188, 0x80, v188
	v_xor_b32_e32 v189, 0x80, v189
	ds_read_b128 v[236:239], v186 offset:49152
	v_exp_f32_e32 v95, v95
	v_add_f32_e32 v170, v170, v92
	v_add_f32_e32 v171, v171, v93
	s_nop 0
	v_add_f32_e32 v170, v170, v94
	v_add_f32_e32 v171, v171, v95
	s_waitcnt lgkmcnt(1)
	v_mfma_f32_32x32x16_bf16 v[220:235], v[240:243], v[116:119], v[220:235]
	ds_read_b128 v[240:243], v186 offset:57344
	v_add_f32_e32 v249, v170, v171
	v_mov_b32_e32 v170, v249
	s_nop 1
	s_waitcnt lgkmcnt(1)
	v_mfma_f32_32x32x16_bf16 v[204:219], v[236:239], v[120:123], v[204:219]
	ds_read_b128 v[236:239], v187 offset:49152
	v_permlane32_swap_b32_e32 v249, v170
	v_cvt_pk_bf16_f32 v64, v64, v65
	v_cvt_pk_bf16_f32 v65, v66, v67
	v_cvt_pk_bf16_f32 v66, v68, v69
	s_waitcnt lgkmcnt(1)
	v_mfma_f32_32x32x16_bf16 v[220:235], v[240:243], v[120:123], v[220:235]
	ds_read_b128 v[240:243], v187 offset:57344
	v_cvt_pk_bf16_f32 v67, v70, v71
	v_cvt_pk_bf16_f32 v68, v72, v73
	v_cvt_pk_bf16_f32 v69, v74, v75
	s_waitcnt lgkmcnt(1)
	v_mfma_f32_32x32x16_bf16 v[204:219], v[236:239], v[124:127], v[204:219]
	ds_read_b128 v[236:239], v188 offset:49152
	v_cvt_pk_bf16_f32 v70, v76, v77
	v_cvt_pk_bf16_f32 v71, v78, v79
	v_cvt_pk_bf16_f32 v72, v80, v81
	v_cvt_pk_bf16_f32 v73, v82, v83
	s_waitcnt lgkmcnt(1)
	v_mfma_f32_32x32x16_bf16 v[220:235], v[240:243], v[124:127], v[220:235]
	ds_read_b128 v[240:243], v188 offset:57344
	v_cvt_pk_bf16_f32 v74, v84, v85
	v_cvt_pk_bf16_f32 v75, v86, v87
	v_cvt_pk_bf16_f32 v76, v88, v89
	s_waitcnt lgkmcnt(1)
	v_mfma_f32_32x32x16_bf16 v[204:219], v[236:239], v[128:131], v[204:219]
	ds_read_b128 v[236:239], v189 offset:49152
	v_cvt_pk_bf16_f32 v77, v90, v91
	v_cvt_pk_bf16_f32 v78, v92, v93
	v_cvt_pk_bf16_f32 v79, v94, v95
	v_permlane32_swap_b32_e32 v64, v66
	s_waitcnt lgkmcnt(1)
	v_mfma_f32_32x32x16_bf16 v[220:235], v[240:243], v[128:131], v[220:235]
	ds_read_b128 v[240:243], v189 offset:57344
	v_permlane32_swap_b32_e32 v65, v67
	v_permlane32_swap_b32_e32 v68, v70
	v_permlane32_swap_b32_e32 v69, v71
	v_permlane32_swap_b32_e32 v72, v74
	s_waitcnt lgkmcnt(1)
	v_mfma_f32_32x32x16_bf16 v[204:219], v[236:239], v[132:135], v[204:219]
	v_permlane32_swap_b32_e32 v73, v75
	v_permlane32_swap_b32_e32 v76, v78
	v_permlane32_swap_b32_e32 v77, v79
	s_waitcnt lgkmcnt(0)
	v_mfma_f32_32x32x16_bf16 v[220:235], v[240:243], v[132:135], v[220:235]
	v_add_f32_e32 v171, v249, v170
	v_fmac_f32_e32 v171, v185, v202
	v_mov_b32_e32 v185, v171
	s_waitcnt vmcnt(0)
	v_add_u32_e32 v200, s8, v180
	v_add_u32_e32 v201, s8, v181
	ds_write_b128 v200, v[96:99]
	ds_write_b128 v201, v[100:103]
	s_and_b64 vcc, exec, s[34:35]
	s_cbranch_vccz .Lat_nwe
	ds_write_b128 v182, v[136:139] offset:32768
	ds_write_b128 v182, v[140:143] offset:40960

.Lat_nmo:
	v_add_u32_e32 v184, 0xffffffc0, v184
	v_max_f32_e32 v200, v205, v205
	s_waitcnt lgkmcnt(6)
	v_mfma_f32_32x32x16_bf16 v[32:47], v[64:67], v[80:83], v[32:47]
	ds_read_b64_tr_b16 v[80:81], v165 offset:512
	ds_read_b64_tr_b16 v[82:83], v165 offset:2560
	v_max_f32_e32 v201, v204, v204
	v_max_f32_e32 v200, v201, v200
	v_max3_f32 v200, v200, v206, v207
	v_max3_f32 v200, v200, v208, v209
	v_max3_f32 v200, v200, v210, v211
	s_waitcnt lgkmcnt(6)
	v_mfma_f32_32x32x16_bf16 v[32:47], v[68:71], v[84:87], v[32:47]
	ds_read_b64_tr_b16 v[84:85], v165 offset:4608
	ds_read_b64_tr_b16 v[86:87], v165 offset:6656
	v_max3_f32 v200, v200, v212, v213
	v_max3_f32 v200, v200, v214, v215
	v_max3_f32 v200, v200, v216, v217
	v_max3_f32 v200, v200, v218, v219
	v_max3_f32 v200, v200, v220, v221
	s_waitcnt lgkmcnt(6)
	v_mfma_f32_32x32x16_bf16 v[32:47], v[72:75], v[88:91], v[32:47]
	ds_read_b64_tr_b16 v[88:89], v165 offset:8704
	ds_read_b64_tr_b16 v[90:91], v165 offset:10752
	v_max3_f32 v200, v200, v222, v223
	v_max3_f32 v200, v200, v224, v225
	v_max3_f32 v200, v200, v226, v227
	v_max3_f32 v200, v200, v228, v229
	s_waitcnt lgkmcnt(6)
	v_mfma_f32_32x32x16_bf16 v[32:47], v[76:79], v[92:95], v[32:47]
	ds_read_b64_tr_b16 v[92:93], v165 offset:12800
	ds_read_b64_tr_b16 v[94:95], v165 offset:14848
	v_max3_f32 v200, v200, v230, v231
	v_max3_f32 v200, v200, v232, v233
	v_max3_f32 v200, v200, v234, v235
	v_mov_b32_e32 v201, v200
	s_nop 1
	s_waitcnt lgkmcnt(6)
	v_mfma_f32_32x32x16_bf16 v[48:63], v[64:67], v[80:83], v[48:63]
	ds_read_b64_tr_b16 v[80:81], v165 offset:1024
	ds_read_b64_tr_b16 v[82:83], v165 offset:3072
	v_permlane32_swap_b32_e32 v200, v201
	v_max_f32_e32 v201, v201, v201
	v_max_f32_e32 v200, v200, v200
	v_max_f32_e32 v200, v200, v201
	v_sub_f32_e32 v201, v200, v203
	s_waitcnt lgkmcnt(6)
	v_mfma_f32_32x32x16_bf16 v[48:63], v[68:71], v[84:87], v[48:63]
	ds_read_b64_tr_b16 v[84:85], v165 offset:5120
	ds_read_b64_tr_b16 v[86:87], v165 offset:7168
	v_mul_f32_e32 v201, 0x3db504f3, v201
	v_cmp_ge_f32_e32 vcc, 0x41000000, v201
	v_max_f32_e32 v201, v203, v203
	v_max_f32_e32 v200, v201, v200
	s_waitcnt lgkmcnt(6)
	v_mfma_f32_32x32x16_bf16 v[48:63], v[72:75], v[88:91], v[48:63]
	ds_read_b64_tr_b16 v[88:89], v165 offset:9216
	ds_read_b64_tr_b16 v[90:91], v165 offset:11264
	v_sub_f32_e32 v201, v203, v200
	v_mul_f32_e32 v201, 0x3e0293ee, v201
	v_exp_f32_e32 v201, v201
	s_cmp_eq_u64 vcc, exec
	s_cselect_b64 s[44:45], -1, 0
	s_waitcnt lgkmcnt(6)
	v_mfma_f32_32x32x16_bf16 v[48:63], v[76:79], v[92:95], v[48:63]
	ds_read_b64_tr_b16 v[92:93], v165 offset:13312
	ds_read_b64_tr_b16 v[94:95], v165 offset:15360
	v_cndmask_b32_e64 v202, v201, 1.0, s[44:45]
	v_cndmask_b32_e64 v203, v200, v203, s[44:45]
	v_mul_f32_e32 v248, 0xbe0293ee, v203
	v_pk_fma_f32 v[204:205], v[204:205], s[10:11], v[248:249] op_sel_hi:[1,0,0]
	v_pk_fma_f32 v[206:207], v[206:207], s[10:11], v[248:249] op_sel_hi:[1,0,0]
	s_waitcnt lgkmcnt(6)
	v_mfma_f32_32x32x16_bf16 v[16:31], v[64:67], v[80:83], v[16:31]
	ds_read_b64_tr_b16 v[80:81], v165 offset:1536
	ds_read_b64_tr_b16 v[82:83], v165 offset:3584
	v_pk_fma_f32 v[208:209], v[208:209], s[10:11], v[248:249] op_sel_hi:[1,0,0]
	v_pk_fma_f32 v[210:211], v[210:211], s[10:11], v[248:249] op_sel_hi:[1,0,0]
	v_pk_fma_f32 v[212:213], v[212:213], s[10:11], v[248:249] op_sel_hi:[1,0,0]
	v_pk_fma_f32 v[214:215], v[214:215], s[10:11], v[248:249] op_sel_hi:[1,0,0]
	s_waitcnt lgkmcnt(6)
	v_mfma_f32_32x32x16_bf16 v[16:31], v[68:71], v[84:87], v[16:31]
	ds_read_b64_tr_b16 v[84:85], v165 offset:5632
	ds_read_b64_tr_b16 v[86:87], v165 offset:7680
	v_pk_fma_f32 v[216:217], v[216:217], s[10:11], v[248:249] op_sel_hi:[1,0,0]
	v_pk_fma_f32 v[218:219], v[218:219], s[10:11], v[248:249] op_sel_hi:[1,0,0]
	v_pk_fma_f32 v[220:221], v[220:221], s[10:11], v[248:249] op_sel_hi:[1,0,0]
	v_pk_fma_f32 v[222:223], v[222:223], s[10:11], v[248:249] op_sel_hi:[1,0,0]
	v_pk_fma_f32 v[224:225], v[224:225], s[10:11], v[248:249] op_sel_hi:[1,0,0]
	s_waitcnt lgkmcnt(6)
	v_mfma_f32_32x32x16_bf16 v[16:31], v[72:75], v[88:91], v[16:31]
	ds_read_b64_tr_b16 v[88:89], v165 offset:9728
	ds_read_b64_tr_b16 v[90:91], v165 offset:11776
	v_pk_fma_f32 v[226:227], v[226:227], s[10:11], v[248:249] op_sel_hi:[1,0,0]
	v_pk_fma_f32 v[228:229], v[228:229], s[10:11], v[248:249] op_sel_hi:[1,0,0]
	v_pk_fma_f32 v[230:231], v[230:231], s[10:11], v[248:249] op_sel_hi:[1,0,0]
	v_pk_fma_f32 v[232:233], v[232:233], s[10:11], v[248:249] op_sel_hi:[1,0,0]
	v_pk_fma_f32 v[234:235], v[234:235], s[10:11], v[248:249] op_sel_hi:[1,0,0]
	s_waitcnt lgkmcnt(6)
	v_mfma_f32_32x32x16_bf16 v[16:31], v[76:79], v[92:95], v[16:31]
	ds_read_b64_tr_b16 v[92:93], v165 offset:13824
	ds_read_b64_tr_b16 v[94:95], v165 offset:15872
	v_exp_f32_e32 v204, v204
	v_exp_f32_e32 v205, v205
	v_exp_f32_e32 v206, v206
	v_exp_f32_e32 v207, v207
	s_waitcnt lgkmcnt(6)
	v_mfma_f32_32x32x16_bf16 v[0:15], v[64:67], v[80:83], v[0:15]
	v_exp_f32_e32 v208, v208
	v_exp_f32_e32 v209, v209
	v_add_f32_e32 v170, v204, v206
	v_add_f32_e32 v171, v205, v207
	v_exp_f32_e32 v210, v210
	v_exp_f32_e32 v211, v211
	s_waitcnt lgkmcnt(4)
	v_mfma_f32_32x32x16_bf16 v[0:15], v[68:71], v[84:87], v[0:15]
	v_add_f32_e32 v170, v170, v208
	v_add_f32_e32 v171, v171, v209
	v_exp_f32_e32 v212, v212
	v_exp_f32_e32 v213, v213
	v_add_f32_e32 v170, v170, v210
	v_add_f32_e32 v171, v171, v211
	v_exp_f32_e32 v214, v214
	s_waitcnt lgkmcnt(2)
	v_mfma_f32_32x32x16_bf16 v[0:15], v[72:75], v[88:91], v[0:15]
	v_exp_f32_e32 v215, v215
	v_add_f32_e32 v170, v170, v212
	v_add_f32_e32 v171, v171, v213
	v_exp_f32_e32 v216, v216
	v_exp_f32_e32 v217, v217
	s_waitcnt lgkmcnt(0)
	v_mfma_f32_32x32x16_bf16 v[0:15], v[76:79], v[92:95], v[0:15]
	v_add_f32_e32 v170, v170, v214
	v_add_f32_e32 v171, v171, v215
	v_exp_f32_e32 v218, v218
	v_exp_f32_e32 v219, v219
	v_add_f32_e32 v170, v170, v216
	v_add_f32_e32 v171, v171, v217
	v_cmp_gt_f32_e32 vcc, 1.0, v202
	s_cbranch_vccz .Lat_nro
	s_nop 7
	s_nop 7
	s_and_saveexec_b64 s[4:5], s[0:1]
	ds_write_b32 v183, v202
	s_or_b64 exec, exec, s[4:5]
	s_waitcnt lgkmcnt(0)
	ds_read_b128 v[244:247], v177 offset:0
	s_waitcnt lgkmcnt(0)
	v_pk_mul_f32 v[32:33], v[32:33], v[244:245]
	v_pk_mul_f32 v[34:35], v[34:35], v[246:247]
	v_pk_mul_f32 v[48:49], v[48:49], v[244:245]
	v_pk_mul_f32 v[50:51], v[50:51], v[246:247]
	v_pk_mul_f32 v[16:17], v[16:17], v[244:245]
	v_pk_mul_f32 v[18:19], v[18:19], v[246:247]
	v_pk_mul_f32 v[0:1], v[0:1], v[244:245]
	v_pk_mul_f32 v[2:3], v[2:3], v[246:247]
	ds_read_b128 v[244:247], v177 offset:32
	s_waitcnt lgkmcnt(0)
	v_pk_mul_f32 v[36:37], v[36:37], v[244:245]
	v_pk_mul_f32 v[38:39], v[38:39], v[246:247]
	v_pk_mul_f32 v[52:53], v[52:53], v[244:245]
	v_pk_mul_f32 v[54:55], v[54:55], v[246:247]
	v_pk_mul_f32 v[20:21], v[20:21], v[244:245]
	v_pk_mul_f32 v[22:23], v[22:23], v[246:247]
	v_pk_mul_f32 v[4:5], v[4:5], v[244:245]
	v_pk_mul_f32 v[6:7], v[6:7], v[246:247]
	ds_read_b128 v[244:247], v177 offset:64
	s_waitcnt lgkmcnt(0)
	v_pk_mul_f32 v[40:41], v[40:41], v[244:245]
	v_pk_mul_f32 v[42:43], v[42:43], v[246:247]
	v_pk_mul_f32 v[56:57], v[56:57], v[244:245]
	v_pk_mul_f32 v[58:59], v[58:59], v[246:247]
	v_pk_mul_f32 v[24:25], v[24:25], v[244:245]
	v_pk_mul_f32 v[26:27], v[26:27], v[246:247]
	v_pk_mul_f32 v[8:9], v[8:9], v[244:245]
	v_pk_mul_f32 v[10:11], v[10:11], v[246:247]
	ds_read_b128 v[244:247], v177 offset:96
	s_waitcnt lgkmcnt(0)
	v_pk_mul_f32 v[44:45], v[44:45], v[244:245]
	v_pk_mul_f32 v[46:47], v[46:47], v[246:247]
	v_pk_mul_f32 v[60:61], v[60:61], v[244:245]
	v_pk_mul_f32 v[62:63], v[62:63], v[246:247]
	v_pk_mul_f32 v[28:29], v[28:29], v[244:245]
	v_pk_mul_f32 v[30:31], v[30:31], v[246:247]
	v_pk_mul_f32 v[12:13], v[12:13], v[244:245]
	v_pk_mul_f32 v[14:15], v[14:15], v[246:247]
.Lat_nro:
	s_waitcnt lgkmcnt(0)
	s_barrier
	v_xor_b32_e32 v186, 0x80, v186
	v_xor_b32_e32 v187, 0x80, v187
	v_xor_b32_e32 v188, 0x80, v188
	v_xor_b32_e32 v189, 0x80, v189
	ds_read_b128 v[236:239], v186 offset:32768
	ds_read_b128 v[240:243], v186 offset:40960
	v_cvt_f32_u32_e32 v64, s13
	v_mov_b32_e32 v165, v164
	v_fma_f32 v64, v172, v64, v179
	v_add_f32_e32 v68, v173, v64
	v_add_f32_e32 v72, v173, v68
	v_add_f32_e32 v76, v173, v72
	v_add_f32_e32 v65, v172, v64
	v_add_f32_e32 v69, v172, v68
	v_add_f32_e32 v73, v172, v72
	v_add_f32_e32 v77, v172, v76
	v_pk_add_f32 v[66:67], v[162:163], v[64:65] op_sel_hi:[1,0]
	v_pk_add_f32 v[70:71], v[162:163], v[68:69] op_sel_hi:[1,0]
	v_pk_add_f32 v[74:75], v[162:163], v[72:73] op_sel_hi:[1,0]
	v_pk_add_f32 v[78:79], v[162:163], v[76:77] op_sel_hi:[1,0]
	v_pk_add_f32 v[82:83], v[164:165], v[66:67]
	v_pk_add_f32 v[80:81], v[166:167], v[64:65]
	v_pk_add_f32 v[86:87], v[164:165], v[70:71]
	v_pk_add_f32 v[84:85], v[164:165], v[68:69]
	v_pk_add_f32 v[90:91], v[164:165], v[74:75]
	v_pk_add_f32 v[88:89], v[164:165], v[72:73]
	v_pk_add_f32 v[94:95], v[164:165], v[78:79]
	v_pk_add_f32 v[92:93], v[164:165], v[76:77]
	s_addk_i32 s13, 0x40
	v_exp_f32_e32 v220, v220
	s_waitcnt lgkmcnt(1)
	v_mfma_f32_32x32x16_bf16 v[64:79], v[236:239], v[104:107], v[64:79]
	ds_read_b128 v[236:239], v187 offset:32768
	v_exp_f32_e32 v221, v221
	v_add_f32_e32 v170, v170, v218
	v_add_f32_e32 v171, v171, v219
	v_exp_f32_e32 v222, v222
	s_waitcnt lgkmcnt(1)
	v_mfma_f32_32x32x16_bf16 v[80:95], v[240:243], v[104:107], v[80:95]
	ds_read_b128 v[240:243], v187 offset:40960
	v_exp_f32_e32 v223, v223
	v_add_f32_e32 v170, v170, v220
	v_add_f32_e32 v171, v171, v221
	v_exp_f32_e32 v224, v224
	v_exp_f32_e32 v225, v225
	s_waitcnt lgkmcnt(1)
	v_mfma_f32_32x32x16_bf16 v[64:79], v[236:239], v[108:111], v[64:79]
	ds_read_b128 v[236:239], v188 offset:32768
	v_add_f32_e32 v170, v170, v222
	v_add_f32_e32 v171, v171, v223
	v_exp_f32_e32 v226, v226
	v_exp_f32_e32 v227, v227
	s_waitcnt lgkmcnt(1)
	v_mfma_f32_32x32x16_bf16 v[80:95], v[240:243], v[108:111], v[80:95]
	ds_read_b128 v[240:243], v188 offset:40960
	v_add_f32_e32 v170, v170, v224
	v_add_f32_e32 v171, v171, v225
	v_exp_f32_e32 v228, v228
	v_exp_f32_e32 v229, v229
	v_add_f32_e32 v170, v170, v226
	v_add_f32_e32 v171, v171, v227
	s_waitcnt lgkmcnt(1)
	v_mfma_f32_32x32x16_bf16 v[64:79], v[236:239], v[112:115], v[64:79]
	ds_read_b128 v[236:239], v189 offset:32768
	v_exp_f32_e32 v230, v230
	v_exp_f32_e32 v231, v231
	v_add_f32_e32 v170, v170, v228
	v_add_f32_e32 v171, v171, v229
	v_exp_f32_e32 v232, v232
	s_waitcnt lgkmcnt(1)
	v_mfma_f32_32x32x16_bf16 v[80:95], v[240:243], v[112:115], v[80:95]
	ds_read_b128 v[240:243], v189 offset:40960
	v_exp_f32_e32 v233, v233
	v_add_f32_e32 v170, v170, v230
	v_add_f32_e32 v171, v171, v231
	v_exp_f32_e32 v234, v234
	s_waitcnt lgkmcnt(1)
	v_mfma_f32_32x32x16_bf16 v[64:79], v[236:239], v[116:119], v[64:79]
	v_xor_b32_e32 v186, 0x80, v186
	v_xor_b32_e32 v187, 0x80, v187
	v_xor_b32_e32 v188, 0x80, v188
	v_xor_b32_e32 v189, 0x80, v189
	ds_read_b128 v[236:239], v186 offset:32768
	v_exp_f32_e32 v235, v235
	v_add_f32_e32 v170, v170, v232
	v_add_f32_e32 v171, v171, v233
	s_nop 0
	v_add_f32_e32 v170, v170, v234
	v_add_f32_e32 v171, v171, v235
	s_waitcnt lgkmcnt(1)
	v_mfma_f32_32x32x16_bf16 v[80:95], v[240:243], v[116:119], v[80:95]
	ds_read_b128 v[240:243], v186 offset:40960
	v_add_f32_e32 v249, v170, v171
	v_mov_b32_e32 v170, v249
	s_nop 1
	s_waitcnt lgkmcnt(1)
	v_mfma_f32_32x32x16_bf16 v[64:79], v[236:239], v[120:123], v[64:79]
	ds_read_b128 v[236:239], v187 offset:32768
	v_permlane32_swap_b32_e32 v249, v170
	v_cvt_pk_bf16_f32 v204, v204, v205
	v_cvt_pk_bf16_f32 v205, v206, v207
	v_cvt_pk_bf16_f32 v206, v208, v209
	s_waitcnt lgkmcnt(1)
	v_mfma_f32_32x32x16_bf16 v[80:95], v[240:243], v[120:123], v[80:95]
	ds_read_b128 v[240:243], v187 offset:40960
	v_cvt_pk_bf16_f32 v207, v210, v211
	v_cvt_pk_bf16_f32 v208, v212, v213
	v_cvt_pk_bf16_f32 v209, v214, v215
	s_waitcnt lgkmcnt(1)
	v_mfma_f32_32x32x16_bf16 v[64:79], v[236:239], v[124:127], v[64:79]
	ds_read_b128 v[236:239], v188 offset:32768
	v_cvt_pk_bf16_f32 v210, v216, v217
	v_cvt_pk_bf16_f32 v211, v218, v219
	v_cvt_pk_bf16_f32 v212, v220, v221
	v_cvt_pk_bf16_f32 v213, v222, v223
	s_waitcnt lgkmcnt(1)
	v_mfma_f32_32x32x16_bf16 v[80:95], v[240:243], v[124:127], v[80:95]
	ds_read_b128 v[240:243], v188 offset:40960
	v_cvt_pk_bf16_f32 v214, v224, v225
	v_cvt_pk_bf16_f32 v215, v226, v227
	v_cvt_pk_bf16_f32 v216, v228, v229
	s_waitcnt lgkmcnt(1)
	v_mfma_f32_32x32x16_bf16 v[64:79], v[236:239], v[128:131], v[64:79]
	ds_read_b128 v[236:239], v189 offset:32768
	v_cvt_pk_bf16_f32 v217, v230, v231
	v_cvt_pk_bf16_f32 v218, v232, v233
	v_cvt_pk_bf16_f32 v219, v234, v235
	v_permlane32_swap_b32_e32 v204, v206
	s_waitcnt lgkmcnt(1)
	v_mfma_f32_32x32x16_bf16 v[80:95], v[240:243], v[128:131], v[80:95]
	ds_read_b128 v[240:243], v189 offset:40960
	v_permlane32_swap_b32_e32 v205, v207
	v_permlane32_swap_b32_e32 v208, v210
	v_permlane32_swap_b32_e32 v209, v211
	v_permlane32_swap_b32_e32 v212, v214
	s_waitcnt lgkmcnt(1)
	v_mfma_f32_32x32x16_bf16 v[64:79], v[236:239], v[132:135], v[64:79]
	v_permlane32_swap_b32_e32 v213, v215
	v_permlane32_swap_b32_e32 v216, v218
	v_permlane32_swap_b32_e32 v217, v219
	s_waitcnt lgkmcnt(0)
	v_mfma_f32_32x32x16_bf16 v[80:95], v[240:243], v[132:135], v[80:95]
	v_add_f32_e32 v171, v249, v170
	v_fmac_f32_e32 v171, v185, v202
	v_mov_b32_e32 v185, v171
	s_waitcnt vmcnt(0)
	s_and_b64 vcc, exec, s[34:35]
	s_cbranch_vccz .Lat_nwo
	v_add_u32_e32 v200, s8, v180
	v_add_u32_e32 v201, s8, v181
	ds_write_b128 v200, v[96:99]
	ds_write_b128 v201, v[100:103]
	ds_write_b128 v182, v[136:139] offset:49152
	ds_write_b128 v182, v[140:143] offset:57344
